# mem_attn prompt rows: K and V^T fragments loaded once per workgroup and staged in LDS (fragment order), all 8 waves ds_read them
# speedup vs baseline: 1.0158x; 1.0124x over previous
; #define LAS __attribute__((address_space(3)))
; __device__ __forceinline__ int opaque_tid(int wv) { int t = wv * 64 + (int)__builtin_amdgcn_mbcnt_hi(~0u, __builtin_amdgcn_mbcnt_lo(~0u, 0u)); asm volatile("" : "+v"(t)); return t; }
; __device__ __forceinline__ void mem_attn_phase(int wv, const Args& A, LAS unsigned char* lds, int G) {
;     const int tid = opaque_tid(wv), lane = tid & 63, w = tid >> 6, fr = lane & 15, fq = lane >> 4;
;     unsigned char* ws = A.ws;
;     const h16* MQ = (const h16*)(ws + WS_MQ); h16* MO = (h16*)(ws + WS_MO);
;     LAS h16* Pw = (LAS h16*)(lds + w * 8448);
;     for (int wu = blockIdx.x * 8 + w; wu < (MT / 16) * 4; wu += G * 8) {
;         const int blk = wu >> 3; const int h = blk & 3, tile = (blk >> 2) * 8 + (wu & 7); const size_t row0 = (size_t)tile * 16;
;         const h16* Kb; const h16* VTb;
;         if (row0 < NP) { const int b = (int)(row0 >> 14); Kb = (const h16*)(ws + WS_MK16) + (size_t)b * 256 * 512; VTb = (const h16*)(ws + WS_MVT) + (size_t)(b * 4 + h) * 32768; }
;         else { const int bs = (int)((row0 - NP) >> 6); Kb = (const h16*)(ws + WS_CMK) + (size_t)bs * 256 * 512; VTb = (const h16*)(ws + WS_CMVT) + (size_t)(bs * 4 + h) * 32768; }
;         h16x8 qf[4];
; #pragma unroll
;         for (int ks = 0; ks < 4; ++ks) qf[ks] = __builtin_bit_cast(h16x8, *(const u32x4*)(MQ + (row0 + fr) * 512 + h * 128 + ks * 32 + fq * 8));
;         f32x4 lg[16]; float m = -INFINITY;
; #pragma unroll
;         for (int kt = 0; kt < 16; ++kt) { f32x4 a = {0.f, 0.f, 0.f, 0.f};
; #pragma unroll
;             for (int ks = 0; ks < 4; ++ks) { const h16x8 kf = __builtin_bit_cast(h16x8, *(const u32x4*)(Kb + (size_t)(kt * 16 + fr) * 512 + h * 128 + ks * 32 + fq * 8)); a = __builtin_amdgcn_mfma_f32_16x16x32_f16(kf, qf[ks], a, 0, 0, 0); }
;             lg[kt] = a; m = fmaxf(m, fmaxf(fmaxf(a[0], a[1]), fmaxf(a[2], a[3]))); }
.LBB0_2399:
	s_or_b64 exec, exec, s[6:7]
	s_waitcnt lgkmcnt(0)
	v_mov_b32_e32 v0, v170
	s_barrier
	v_mbcnt_lo_u32_b32 v0, -1, 0
	v_mbcnt_hi_u32_b32 v0, -1, v0
	v_and_b32_e32 v1, 15, v0
	v_lshrrev_b32_e32 v2, 4, v0
	v_ashrrev_i32_e32 v64, 6, v170
	s_nop 0
	v_readfirstlane_b32 s70, v64
	v_lshlrev_b32_e32 v4, 10, v1
	v_lshl_add_u32 v4, v2, 4, v4
	v_lshlrev_b32_e32 v5, 9, v1
	v_lshl_add_u32 v5, v2, 4, v5
	v_lshlrev_b32_e32 v7, 4, v0
	v_add_u32_e32 v7, 0x11000, v7
	s_lshl_b32 s32, s70, 13
	v_add_u32_e32 v6, s32, v7
	s_mul_i32 s32, s70, 0x2100
	v_mul_u32_u24_e32 v8, 0x210, v1
	v_add_u32_e32 v8, s32, v8
	v_lshl_add_u32 v9, v2, 4, v8
	v_lshl_add_u32 v8, v2, 3, v8
	v_lshlrev_b32_e32 v10, 10, v1
	v_lshl_add_u32 v10, v2, 3, v10
	v_xor_b32_e32 v11, 16, v0
	v_lshlrev_b32_e32 v11, 2, v11
	v_xor_b32_e32 v12, 32, v0
	v_lshlrev_b32_e32 v12, 2, v12
	s_mov_b32 s71, 0
.Lma_round:
	s_lshl_b32 s72, s71, 8
	s_add_i32 s73, s2, s72
	s_and_b32 s74, s73, 3
	s_lshr_b32 s75, s73, 2
	s_lshl_b32 s75, s75, 3
	s_add_i32 s75, s75, s70
	s_lshr_b32 s76, s75, 10
	s_lshl_b32 s32, s76, 18
	s_lshl_b32 s33, s74, 8
	s_add_i32 s32, s32, s33
	s_lshl_b32 s33, s70, 15
	s_add_i32 s32, s32, s33
	s_add_u32 s78, s44, 0x3cc4d000
	s_addc_u32 s79, s45, 0
	s_add_u32 s78, s78, s32
	s_addc_u32 s79, s79, 0
	s_add_u32 s88, s78, 0x4000
	s_addc_u32 s89, s79, 0
	s_lshl_b32 s32, s76, 2
	s_add_i32 s32, s32, s74
	s_lshl_b32 s32, s32, 16
	s_lshl_b32 s33, s70, 13
	s_add_i32 s32, s32, s33
	s_add_u32 s90, s44, 0x3cccd000
	s_addc_u32 s91, s45, 0
	s_add_u32 s90, s90, s32
	s_addc_u32 s91, s91, 0
	s_lshl_b32 s32, s75, 14
	s_lshl_b32 s33, s74, 8
	s_add_i32 s32, s32, s33
	s_add_u32 s92, s44, 0x324c1000
	s_addc_u32 s93, s45, 0
	s_add_u32 s92, s92, s32
	s_addc_u32 s93, s93, 0
	s_add_u32 s94, s44, 0x34541000
	s_addc_u32 s95, s45, 0
	s_add_u32 s94, s94, s32
	s_addc_u32 s95, s95, 0
	global_load_dwordx4 v[32:35], v4, s[78:79]
	global_load_dwordx4 v[36:39], v4, s[78:79] offset:64
	global_load_dwordx4 v[40:43], v4, s[78:79] offset:128
	global_load_dwordx4 v[44:47], v4, s[78:79] offset:192
	global_load_dwordx4 v[48:51], v4, s[88:89]
	global_load_dwordx4 v[52:55], v4, s[88:89] offset:64
	global_load_dwordx4 v[56:59], v4, s[88:89] offset:128
	global_load_dwordx4 v[60:63], v4, s[88:89] offset:192
	global_load_dwordx4 v[16:19], v4, s[92:93]
	global_load_dwordx4 v[20:23], v4, s[92:93] offset:64
	global_load_dwordx4 v[24:27], v4, s[92:93] offset:128
	global_load_dwordx4 v[28:31], v4, s[92:93] offset:192
	global_load_dwordx4 v[182:185], v5, s[90:91]
	global_load_dwordx4 v[186:189], v5, s[90:91] offset:64
	global_load_dwordx4 v[190:193], v5, s[90:91] offset:128
	global_load_dwordx4 v[194:197], v5, s[90:91] offset:192
	global_load_dwordx4 v[198:201], v5, s[90:91] offset:256
	global_load_dwordx4 v[202:205], v5, s[90:91] offset:320
	global_load_dwordx4 v[206:209], v5, s[90:91] offset:384
	global_load_dwordx4 v[210:213], v5, s[90:91] offset:448
	s_cmp_eq_u32 s71, 0
	s_cbranch_scc1 .Lma_nobar
	s_barrier
.Lma_nobar:
	s_waitcnt vmcnt(19)
	ds_write_b128 v6, v[32:35]
	s_waitcnt vmcnt(18)
	ds_write_b128 v6, v[36:39] offset:1024
	s_waitcnt vmcnt(17)
	ds_write_b128 v6, v[40:43] offset:2048
	s_waitcnt vmcnt(16)
	ds_write_b128 v6, v[44:47] offset:3072
	s_waitcnt vmcnt(15)
	ds_write_b128 v6, v[48:51] offset:4096
	s_waitcnt vmcnt(14)
	ds_write_b128 v6, v[52:55] offset:5120
	s_waitcnt vmcnt(13)
	ds_write_b128 v6, v[56:59] offset:6144
	s_waitcnt vmcnt(12)
	ds_write_b128 v6, v[60:63] offset:7168
	s_waitcnt lgkmcnt(0)
	s_barrier
	s_waitcnt vmcnt(8)
	ds_read_b128 v[32:35], v7
	ds_read_b128 v[36:39], v7 offset:1024
	ds_read_b128 v[40:43], v7 offset:2048
	ds_read_b128 v[44:47], v7 offset:3072
	ds_read_b128 v[48:51], v7 offset:4096
	ds_read_b128 v[52:55], v7 offset:5120
	ds_read_b128 v[56:59], v7 offset:6144
	ds_read_b128 v[60:63], v7 offset:7168
	ds_read_b128 v[240:243], v7 offset:8192
	ds_read_b128 v[244:247], v7 offset:9216
	ds_read_b128 v[248:251], v7 offset:10240
	ds_read_b128 v[252:255], v7 offset:11264
	s_waitcnt lgkmcnt(11)
	v_mfma_f32_16x16x32_f16 v[96:99], v[32:35], v[16:19], 0
	ds_read_b128 v[32:35], v7 offset:12288
	s_waitcnt lgkmcnt(11)
	v_mfma_f32_16x16x32_f16 v[96:99], v[36:39], v[20:23], v[96:99]
	ds_read_b128 v[36:39], v7 offset:13312
	s_waitcnt lgkmcnt(11)
	v_mfma_f32_16x16x32_f16 v[96:99], v[40:43], v[24:27], v[96:99]
	ds_read_b128 v[40:43], v7 offset:14336
	s_waitcnt lgkmcnt(11)
	v_mfma_f32_16x16x32_f16 v[96:99], v[44:47], v[28:31], v[96:99]
	ds_read_b128 v[44:47], v7 offset:15360
	s_waitcnt lgkmcnt(11)
	v_mfma_f32_16x16x32_f16 v[100:103], v[48:51], v[16:19], 0
	ds_read_b128 v[48:51], v7 offset:16384
	s_waitcnt lgkmcnt(11)
	v_mfma_f32_16x16x32_f16 v[100:103], v[52:55], v[20:23], v[100:103]
	ds_read_b128 v[52:55], v7 offset:17408
	s_waitcnt lgkmcnt(11)
	v_mfma_f32_16x16x32_f16 v[100:103], v[56:59], v[24:27], v[100:103]
	ds_read_b128 v[56:59], v7 offset:18432
	s_waitcnt lgkmcnt(11)
	v_mfma_f32_16x16x32_f16 v[100:103], v[60:63], v[28:31], v[100:103]
	ds_read_b128 v[60:63], v7 offset:19456
	s_waitcnt lgkmcnt(11)
	v_mfma_f32_16x16x32_f16 v[104:107], v[240:243], v[16:19], 0
	ds_read_b128 v[240:243], v7 offset:20480
	s_waitcnt lgkmcnt(11)
	v_mfma_f32_16x16x32_f16 v[104:107], v[244:247], v[20:23], v[104:107]
	ds_read_b128 v[244:247], v7 offset:21504
	s_waitcnt lgkmcnt(11)
	v_mfma_f32_16x16x32_f16 v[104:107], v[248:251], v[24:27], v[104:107]
	ds_read_b128 v[248:251], v7 offset:22528
	s_waitcnt lgkmcnt(11)
	v_mfma_f32_16x16x32_f16 v[104:107], v[252:255], v[28:31], v[104:107]
	ds_read_b128 v[252:255], v7 offset:23552
	s_waitcnt lgkmcnt(11)
	v_mfma_f32_16x16x32_f16 v[108:111], v[32:35], v[16:19], 0
	ds_read_b128 v[32:35], v7 offset:24576
	s_waitcnt lgkmcnt(11)
; __device__ __forceinline__ void mem_attn_phase(int wv, const Args& A, LAS unsigned char* lds, int G) {
;     ...
;         for (int kt = 0; kt < 16; ++kt) { f32x4 a = {0.f, 0.f, 0.f, 0.f};
; #pragma unroll
;             for (int ks = 0; ks < 4; ++ks) { const h16x8 kf = __builtin_bit_cast(h16x8, *(const u32x4*)(Kb + (size_t)(kt * 16 + fr) * 512 + h * 128 + ks * 32 + fq * 8)); a = __builtin_amdgcn_mfma_f32_16x16x32_f16(kf, qf[ks], a, 0, 0, 0); }
;             lg[kt] = a; m = fmaxf(m, fmaxf(fmaxf(a[0], a[1]), fmaxf(a[2], a[3]))); }
	v_mfma_f32_16x16x32_f16 v[108:111], v[36:39], v[20:23], v[108:111]
	ds_read_b128 v[36:39], v7 offset:25600
	s_waitcnt lgkmcnt(11)
	v_mfma_f32_16x16x32_f16 v[108:111], v[40:43], v[24:27], v[108:111]
	ds_read_b128 v[40:43], v7 offset:26624
	s_waitcnt lgkmcnt(11)
	v_mfma_f32_16x16x32_f16 v[108:111], v[44:47], v[28:31], v[108:111]
	ds_read_b128 v[44:47], v7 offset:27648
	s_waitcnt lgkmcnt(11)
	v_mfma_f32_16x16x32_f16 v[112:115], v[48:51], v[16:19], 0
	ds_read_b128 v[48:51], v7 offset:28672
	s_waitcnt lgkmcnt(11)
	v_mfma_f32_16x16x32_f16 v[112:115], v[52:55], v[20:23], v[112:115]
	ds_read_b128 v[52:55], v7 offset:29696
	s_waitcnt lgkmcnt(11)
	v_mfma_f32_16x16x32_f16 v[112:115], v[56:59], v[24:27], v[112:115]
	ds_read_b128 v[56:59], v7 offset:30720
	s_waitcnt lgkmcnt(11)
	v_mfma_f32_16x16x32_f16 v[112:115], v[60:63], v[28:31], v[112:115]
	ds_read_b128 v[60:63], v7 offset:31744
	s_waitcnt lgkmcnt(11)
	v_mfma_f32_16x16x32_f16 v[116:119], v[240:243], v[16:19], 0
	ds_read_b128 v[240:243], v7 offset:32768
	s_waitcnt lgkmcnt(11)
	v_mfma_f32_16x16x32_f16 v[116:119], v[244:247], v[20:23], v[116:119]
	ds_read_b128 v[244:247], v7 offset:33792
	s_waitcnt lgkmcnt(11)
	v_mfma_f32_16x16x32_f16 v[116:119], v[248:251], v[24:27], v[116:119]
	ds_read_b128 v[248:251], v7 offset:34816
	s_waitcnt lgkmcnt(11)
	v_mfma_f32_16x16x32_f16 v[116:119], v[252:255], v[28:31], v[116:119]
	ds_read_b128 v[252:255], v7 offset:35840
	s_waitcnt lgkmcnt(11)
	v_mfma_f32_16x16x32_f16 v[120:123], v[32:35], v[16:19], 0
	ds_read_b128 v[32:35], v7 offset:36864
	s_waitcnt lgkmcnt(11)
	v_mfma_f32_16x16x32_f16 v[120:123], v[36:39], v[20:23], v[120:123]
	ds_read_b128 v[36:39], v7 offset:37888
	s_waitcnt lgkmcnt(11)
	v_mfma_f32_16x16x32_f16 v[120:123], v[40:43], v[24:27], v[120:123]
	ds_read_b128 v[40:43], v7 offset:38912
	s_waitcnt lgkmcnt(11)
	v_mfma_f32_16x16x32_f16 v[120:123], v[44:47], v[28:31], v[120:123]
	ds_read_b128 v[44:47], v7 offset:39936
	s_waitcnt lgkmcnt(11)
	v_mfma_f32_16x16x32_f16 v[124:127], v[48:51], v[16:19], 0
	ds_read_b128 v[48:51], v7 offset:40960
	s_waitcnt lgkmcnt(11)
	v_mfma_f32_16x16x32_f16 v[124:127], v[52:55], v[20:23], v[124:127]
	ds_read_b128 v[52:55], v7 offset:41984
	s_waitcnt lgkmcnt(11)
	v_mfma_f32_16x16x32_f16 v[124:127], v[56:59], v[24:27], v[124:127]
	ds_read_b128 v[56:59], v7 offset:43008
	s_waitcnt lgkmcnt(11)
	v_mfma_f32_16x16x32_f16 v[124:127], v[60:63], v[28:31], v[124:127]
	ds_read_b128 v[60:63], v7 offset:44032
	s_waitcnt lgkmcnt(11)
	v_mfma_f32_16x16x32_f16 v[128:131], v[240:243], v[16:19], 0
	ds_read_b128 v[240:243], v7 offset:45056
	s_waitcnt lgkmcnt(11)
	v_mfma_f32_16x16x32_f16 v[128:131], v[244:247], v[20:23], v[128:131]
	ds_read_b128 v[244:247], v7 offset:46080
	s_waitcnt lgkmcnt(11)
	v_mfma_f32_16x16x32_f16 v[128:131], v[248:251], v[24:27], v[128:131]
	ds_read_b128 v[248:251], v7 offset:47104
	s_waitcnt lgkmcnt(11)
	v_mfma_f32_16x16x32_f16 v[128:131], v[252:255], v[28:31], v[128:131]
	ds_read_b128 v[252:255], v7 offset:48128
	s_waitcnt lgkmcnt(11)
	v_mfma_f32_16x16x32_f16 v[132:135], v[32:35], v[16:19], 0
	ds_read_b128 v[32:35], v7 offset:49152
	s_waitcnt lgkmcnt(11)
	v_mfma_f32_16x16x32_f16 v[132:135], v[36:39], v[20:23], v[132:135]
	ds_read_b128 v[36:39], v7 offset:50176
	s_waitcnt lgkmcnt(11)
	v_mfma_f32_16x16x32_f16 v[132:135], v[40:43], v[24:27], v[132:135]
	ds_read_b128 v[40:43], v7 offset:51200
	s_waitcnt lgkmcnt(11)
	v_mfma_f32_16x16x32_f16 v[132:135], v[44:47], v[28:31], v[132:135]
	ds_read_b128 v[44:47], v7 offset:52224
	s_waitcnt lgkmcnt(11)
	v_mfma_f32_16x16x32_f16 v[136:139], v[48:51], v[16:19], 0
	ds_read_b128 v[48:51], v7 offset:53248
	s_waitcnt lgkmcnt(11)
	v_mfma_f32_16x16x32_f16 v[136:139], v[52:55], v[20:23], v[136:139]
	ds_read_b128 v[52:55], v7 offset:54272
	s_waitcnt lgkmcnt(11)
	v_mfma_f32_16x16x32_f16 v[136:139], v[56:59], v[24:27], v[136:139]
	ds_read_b128 v[56:59], v7 offset:55296
	s_waitcnt lgkmcnt(11)
	v_mfma_f32_16x16x32_f16 v[136:139], v[60:63], v[28:31], v[136:139]
	ds_read_b128 v[60:63], v7 offset:56320
	s_waitcnt lgkmcnt(11)
	v_mfma_f32_16x16x32_f16 v[140:143], v[240:243], v[16:19], 0
	ds_read_b128 v[240:243], v7 offset:57344
	s_waitcnt lgkmcnt(11)
	v_mfma_f32_16x16x32_f16 v[140:143], v[244:247], v[20:23], v[140:143]
	ds_read_b128 v[244:247], v7 offset:58368
	s_waitcnt lgkmcnt(11)
	v_mfma_f32_16x16x32_f16 v[140:143], v[248:251], v[24:27], v[140:143]
	ds_read_b128 v[248:251], v7 offset:59392
	s_waitcnt lgkmcnt(11)
	v_mfma_f32_16x16x32_f16 v[140:143], v[252:255], v[28:31], v[140:143]
	ds_read_b128 v[252:255], v7 offset:60416
	s_waitcnt lgkmcnt(11)
	v_mfma_f32_16x16x32_f16 v[144:147], v[32:35], v[16:19], 0
	ds_read_b128 v[32:35], v7 offset:61440
	s_waitcnt lgkmcnt(11)
	v_mfma_f32_16x16x32_f16 v[144:147], v[36:39], v[20:23], v[144:147]
	ds_read_b128 v[36:39], v7 offset:62464
	s_waitcnt lgkmcnt(11)
	v_mfma_f32_16x16x32_f16 v[144:147], v[40:43], v[24:27], v[144:147]
	ds_read_b128 v[40:43], v7 offset:63488
	s_waitcnt lgkmcnt(11)
	v_mfma_f32_16x16x32_f16 v[144:147], v[44:47], v[28:31], v[144:147]
	ds_read_b128 v[44:47], v7 offset:64512
	s_waitcnt lgkmcnt(11)
	v_mfma_f32_16x16x32_f16 v[148:151], v[48:51], v[16:19], 0
	s_waitcnt lgkmcnt(10)
	v_mfma_f32_16x16x32_f16 v[148:151], v[52:55], v[20:23], v[148:151]
	s_waitcnt lgkmcnt(9)
	v_mfma_f32_16x16x32_f16 v[148:151], v[56:59], v[24:27], v[148:151]
	s_waitcnt lgkmcnt(8)
	v_mfma_f32_16x16x32_f16 v[148:151], v[60:63], v[28:31], v[148:151]
	s_waitcnt lgkmcnt(7)
	v_mfma_f32_16x16x32_f16 v[152:155], v[240:243], v[16:19], 0
	s_waitcnt lgkmcnt(6)
	v_mfma_f32_16x16x32_f16 v[152:155], v[244:247], v[20:23], v[152:155]
	s_waitcnt lgkmcnt(5)
; #define LAS __attribute__((address_space(3)))
; __device__ __forceinline__ void mem_attn_phase(int wv, const Args& A, LAS unsigned char* lds, int G) {
;     ...
;         for (int kt = 0; kt < 16; ++kt) { f32x4 a = {0.f, 0.f, 0.f, 0.f};
; #pragma unroll
;             for (int ks = 0; ks < 4; ++ks) { const h16x8 kf = __builtin_bit_cast(h16x8, *(const u32x4*)(Kb + (size_t)(kt * 16 + fr) * 512 + h * 128 + ks * 32 + fq * 8)); a = __builtin_amdgcn_mfma_f32_16x16x32_f16(kf, qf[ks], a, 0, 0, 0); }
;             lg[kt] = a; m = fmaxf(m, fmaxf(fmaxf(a[0], a[1]), fmaxf(a[2], a[3]))); }
;         m = fmaxf(m, __shfl_xor(m, 16)); m = fmaxf(m, __shfl_xor(m, 32));
;         float sm = 0.f;
; #pragma unroll
;         for (int kt = 0; kt < 16; ++kt) { h16x4 p4;
; #pragma unroll
;             for (int r = 0; r < 4; ++r) { const float p = __expf(lg[kt][r] - m); sm += p; p4[r] = (h16)p; }
;             *(LAS u32x2*)(Pw + fr * 264 + kt * 16 + fq * 4) = __builtin_bit_cast(u32x2, p4); }
;         sm += __shfl_xor(sm, 16); sm += __shfl_xor(sm, 32);
	v_mfma_f32_16x16x32_f16 v[152:155], v[248:251], v[24:27], v[152:155]
	s_waitcnt lgkmcnt(4)
	v_mfma_f32_16x16x32_f16 v[152:155], v[252:255], v[28:31], v[152:155]
	s_waitcnt lgkmcnt(3)
	v_mfma_f32_16x16x32_f16 v[156:159], v[32:35], v[16:19], 0
	s_waitcnt lgkmcnt(2)
	v_mfma_f32_16x16x32_f16 v[156:159], v[36:39], v[20:23], v[156:159]
	s_waitcnt lgkmcnt(1)
	v_mfma_f32_16x16x32_f16 v[156:159], v[40:43], v[24:27], v[156:159]
	s_waitcnt lgkmcnt(0)
	v_mfma_f32_16x16x32_f16 v[156:159], v[44:47], v[28:31], v[156:159]
	s_nop 7
	s_nop 1
	v_max3_f32 v13, v96, v97, v98
	v_max3_f32 v13, v13, v99, v100
	v_max3_f32 v13, v13, v101, v102
	v_max3_f32 v13, v13, v103, v104
	v_max3_f32 v13, v13, v105, v106
	v_max3_f32 v13, v13, v107, v108
	v_max3_f32 v13, v13, v109, v110
	v_max3_f32 v13, v13, v111, v112
	v_max3_f32 v13, v13, v113, v114
	v_max3_f32 v13, v13, v115, v116
	v_max3_f32 v13, v13, v117, v118
	v_max3_f32 v13, v13, v119, v120
	v_max3_f32 v13, v13, v121, v122
	v_max3_f32 v13, v13, v123, v124
	v_max3_f32 v13, v13, v125, v126
	v_max3_f32 v13, v13, v127, v128
	v_max3_f32 v13, v13, v129, v130
	v_max3_f32 v13, v13, v131, v132
	v_max3_f32 v13, v13, v133, v134
	v_max3_f32 v13, v13, v135, v136
	v_max3_f32 v13, v13, v137, v138
	v_max3_f32 v13, v13, v139, v140
	v_max3_f32 v13, v13, v141, v142
	v_max3_f32 v13, v13, v143, v144
	v_max3_f32 v13, v13, v145, v146
	v_max3_f32 v13, v13, v147, v148
	v_max3_f32 v13, v13, v149, v150
	v_max3_f32 v13, v13, v151, v152
	v_max3_f32 v13, v13, v153, v154
	v_max3_f32 v13, v13, v155, v156
	v_max3_f32 v13, v13, v157, v158
	v_max_f32_e32 v13, v13, v159
	ds_bpermute_b32 v64, v11, v13
	s_waitcnt lgkmcnt(0)
	v_max_f32_e32 v13, v13, v64
	ds_bpermute_b32 v64, v12, v13
	s_waitcnt lgkmcnt(0)
	v_max_f32_e32 v13, v13, v64
	v_mov_b32_e32 v14, 0
	v_sub_f32_e32 v96, v96, v13
	v_sub_f32_e32 v97, v97, v13
	v_sub_f32_e32 v98, v98, v13
	v_sub_f32_e32 v99, v99, v13
	v_mul_f32_e32 v96, 0x3fb8aa3b, v96
	v_mul_f32_e32 v97, 0x3fb8aa3b, v97
	v_mul_f32_e32 v98, 0x3fb8aa3b, v98
	v_mul_f32_e32 v99, 0x3fb8aa3b, v99
	v_exp_f32_e32 v96, v96
	v_exp_f32_e32 v97, v97
	v_exp_f32_e32 v98, v98
	v_exp_f32_e32 v99, v99
	s_nop 0
	v_add_f32_e32 v14, v14, v96
	v_add_f32_e32 v14, v14, v97
	v_add_f32_e32 v14, v14, v98
	v_add_f32_e32 v14, v14, v99
	v_cvt_pk_f16_f32 v64, v96, v97
	v_cvt_pk_f16_f32 v65, v98, v99
	ds_write_b64 v8, v[64:65]
	v_sub_f32_e32 v100, v100, v13
	v_sub_f32_e32 v101, v101, v13
	v_sub_f32_e32 v102, v102, v13
	v_sub_f32_e32 v103, v103, v13
	v_mul_f32_e32 v100, 0x3fb8aa3b, v100
	v_mul_f32_e32 v101, 0x3fb8aa3b, v101
	v_mul_f32_e32 v102, 0x3fb8aa3b, v102
	v_mul_f32_e32 v103, 0x3fb8aa3b, v103
	v_exp_f32_e32 v100, v100
	v_exp_f32_e32 v101, v101
	v_exp_f32_e32 v102, v102
	v_exp_f32_e32 v103, v103
	s_nop 0
	v_add_f32_e32 v14, v14, v100
	v_add_f32_e32 v14, v14, v101
	v_add_f32_e32 v14, v14, v102
	v_add_f32_e32 v14, v14, v103
	v_cvt_pk_f16_f32 v66, v100, v101
	v_cvt_pk_f16_f32 v67, v102, v103
	ds_write_b64 v8, v[66:67] offset:32
	v_sub_f32_e32 v104, v104, v13
	v_sub_f32_e32 v105, v105, v13
	v_sub_f32_e32 v106, v106, v13
	v_sub_f32_e32 v107, v107, v13
	v_mul_f32_e32 v104, 0x3fb8aa3b, v104
	v_mul_f32_e32 v105, 0x3fb8aa3b, v105
	v_mul_f32_e32 v106, 0x3fb8aa3b, v106
	v_mul_f32_e32 v107, 0x3fb8aa3b, v107
	v_exp_f32_e32 v104, v104
	v_exp_f32_e32 v105, v105
	v_exp_f32_e32 v106, v106
	v_exp_f32_e32 v107, v107
	s_nop 0
	v_add_f32_e32 v14, v14, v104
	v_add_f32_e32 v14, v14, v105
	v_add_f32_e32 v14, v14, v106
	v_add_f32_e32 v14, v14, v107
	v_cvt_pk_f16_f32 v64, v104, v105
	v_cvt_pk_f16_f32 v65, v106, v107
	ds_write_b64 v8, v[64:65] offset:64
	v_sub_f32_e32 v108, v108, v13
	v_sub_f32_e32 v109, v109, v13
	v_sub_f32_e32 v110, v110, v13
	v_sub_f32_e32 v111, v111, v13
	v_mul_f32_e32 v108, 0x3fb8aa3b, v108
	v_mul_f32_e32 v109, 0x3fb8aa3b, v109
	v_mul_f32_e32 v110, 0x3fb8aa3b, v110
	v_mul_f32_e32 v111, 0x3fb8aa3b, v111
	v_exp_f32_e32 v108, v108
	v_exp_f32_e32 v109, v109
	v_exp_f32_e32 v110, v110
	v_exp_f32_e32 v111, v111
	s_nop 0
	v_add_f32_e32 v14, v14, v108
	v_add_f32_e32 v14, v14, v109
	v_add_f32_e32 v14, v14, v110
	v_add_f32_e32 v14, v14, v111
	v_cvt_pk_f16_f32 v66, v108, v109
	v_cvt_pk_f16_f32 v67, v110, v111
	ds_write_b64 v8, v[66:67] offset:96
	v_sub_f32_e32 v112, v112, v13
	v_sub_f32_e32 v113, v113, v13
	v_sub_f32_e32 v114, v114, v13
	v_sub_f32_e32 v115, v115, v13
	v_mul_f32_e32 v112, 0x3fb8aa3b, v112
	v_mul_f32_e32 v113, 0x3fb8aa3b, v113
	v_mul_f32_e32 v114, 0x3fb8aa3b, v114
	v_mul_f32_e32 v115, 0x3fb8aa3b, v115
	v_exp_f32_e32 v112, v112
	v_exp_f32_e32 v113, v113
	v_exp_f32_e32 v114, v114
	v_exp_f32_e32 v115, v115
	s_nop 0
	v_add_f32_e32 v14, v14, v112
	v_add_f32_e32 v14, v14, v113
	v_add_f32_e32 v14, v14, v114
	v_add_f32_e32 v14, v14, v115
	v_cvt_pk_f16_f32 v64, v112, v113
	v_cvt_pk_f16_f32 v65, v114, v115
	ds_write_b64 v8, v[64:65] offset:128
	v_sub_f32_e32 v116, v116, v13
	v_sub_f32_e32 v117, v117, v13
	v_sub_f32_e32 v118, v118, v13
	v_sub_f32_e32 v119, v119, v13
	v_mul_f32_e32 v116, 0x3fb8aa3b, v116
	v_mul_f32_e32 v117, 0x3fb8aa3b, v117
	v_mul_f32_e32 v118, 0x3fb8aa3b, v118
	v_mul_f32_e32 v119, 0x3fb8aa3b, v119
	v_exp_f32_e32 v116, v116
	v_exp_f32_e32 v117, v117
	v_exp_f32_e32 v118, v118
	v_exp_f32_e32 v119, v119
	s_nop 0
	v_add_f32_e32 v14, v14, v116
	v_add_f32_e32 v14, v14, v117
	v_add_f32_e32 v14, v14, v118
	v_add_f32_e32 v14, v14, v119
	v_cvt_pk_f16_f32 v66, v116, v117
	v_cvt_pk_f16_f32 v67, v118, v119
	ds_write_b64 v8, v[66:67] offset:160
	v_sub_f32_e32 v120, v120, v13
	v_sub_f32_e32 v121, v121, v13
	v_sub_f32_e32 v122, v122, v13
	v_sub_f32_e32 v123, v123, v13
	v_mul_f32_e32 v120, 0x3fb8aa3b, v120
	v_mul_f32_e32 v121, 0x3fb8aa3b, v121
	v_mul_f32_e32 v122, 0x3fb8aa3b, v122
; #define LAS __attribute__((address_space(3)))
; __device__ __forceinline__ void mem_attn_phase(int wv, const Args& A, LAS unsigned char* lds, int G) {
;     ...
;         for (int kt = 0; kt < 16; ++kt) { h16x4 p4;
; #pragma unroll
;             for (int r = 0; r < 4; ++r) { const float p = __expf(lg[kt][r] - m); sm += p; p4[r] = (h16)p; }
;             *(LAS u32x2*)(Pw + fr * 264 + kt * 16 + fq * 4) = __builtin_bit_cast(u32x2, p4); }
;         sm += __shfl_xor(sm, 16); sm += __shfl_xor(sm, 32);
;         const float inv = 1.f / sm;
; #pragma unroll
;         for (int db = 0; db < 8; ++db) { f32x4 o = {0.f, 0.f, 0.f, 0.f};
; #pragma unroll
;             for (int ks = 0; ks < 8; ++ks) { const h16x8 vf = __builtin_bit_cast(h16x8, *(const u32x4*)(VTb + (size_t)(db * 16 + fr) * 256 + ks * 32 + fq * 8));
;                 const h16x8 pf = *(const LAS h16x8*)(Pw + fr * 264 + ks * 32 + fq * 8); o = __builtin_amdgcn_mfma_f32_16x16x32_f16(vf, pf, o, 0, 0, 0); }
	v_mul_f32_e32 v123, 0x3fb8aa3b, v123
	v_exp_f32_e32 v120, v120
	v_exp_f32_e32 v121, v121
	v_exp_f32_e32 v122, v122
	v_exp_f32_e32 v123, v123
	s_nop 0
	v_add_f32_e32 v14, v14, v120
	v_add_f32_e32 v14, v14, v121
	v_add_f32_e32 v14, v14, v122
	v_add_f32_e32 v14, v14, v123
	v_cvt_pk_f16_f32 v64, v120, v121
	v_cvt_pk_f16_f32 v65, v122, v123
	ds_write_b64 v8, v[64:65] offset:192
	v_sub_f32_e32 v124, v124, v13
	v_sub_f32_e32 v125, v125, v13
	v_sub_f32_e32 v126, v126, v13
	v_sub_f32_e32 v127, v127, v13
	v_mul_f32_e32 v124, 0x3fb8aa3b, v124
	v_mul_f32_e32 v125, 0x3fb8aa3b, v125
	v_mul_f32_e32 v126, 0x3fb8aa3b, v126
	v_mul_f32_e32 v127, 0x3fb8aa3b, v127
	v_exp_f32_e32 v124, v124
	v_exp_f32_e32 v125, v125
	v_exp_f32_e32 v126, v126
	v_exp_f32_e32 v127, v127
	s_nop 0
	v_add_f32_e32 v14, v14, v124
	v_add_f32_e32 v14, v14, v125
	v_add_f32_e32 v14, v14, v126
	v_add_f32_e32 v14, v14, v127
	v_cvt_pk_f16_f32 v66, v124, v125
	v_cvt_pk_f16_f32 v67, v126, v127
	ds_write_b64 v8, v[66:67] offset:224
	v_sub_f32_e32 v128, v128, v13
	v_sub_f32_e32 v129, v129, v13
	v_sub_f32_e32 v130, v130, v13
	v_sub_f32_e32 v131, v131, v13
	v_mul_f32_e32 v128, 0x3fb8aa3b, v128
	v_mul_f32_e32 v129, 0x3fb8aa3b, v129
	v_mul_f32_e32 v130, 0x3fb8aa3b, v130
	v_mul_f32_e32 v131, 0x3fb8aa3b, v131
	v_exp_f32_e32 v128, v128
	v_exp_f32_e32 v129, v129
	v_exp_f32_e32 v130, v130
	v_exp_f32_e32 v131, v131
	s_nop 0
	v_add_f32_e32 v14, v14, v128
	v_add_f32_e32 v14, v14, v129
	v_add_f32_e32 v14, v14, v130
	v_add_f32_e32 v14, v14, v131
	v_cvt_pk_f16_f32 v64, v128, v129
	v_cvt_pk_f16_f32 v65, v130, v131
	ds_write_b64 v8, v[64:65] offset:256
	v_sub_f32_e32 v132, v132, v13
	v_sub_f32_e32 v133, v133, v13
	v_sub_f32_e32 v134, v134, v13
	v_sub_f32_e32 v135, v135, v13
	v_mul_f32_e32 v132, 0x3fb8aa3b, v132
	v_mul_f32_e32 v133, 0x3fb8aa3b, v133
	v_mul_f32_e32 v134, 0x3fb8aa3b, v134
	v_mul_f32_e32 v135, 0x3fb8aa3b, v135
	v_exp_f32_e32 v132, v132
	v_exp_f32_e32 v133, v133
	v_exp_f32_e32 v134, v134
	v_exp_f32_e32 v135, v135
	s_nop 0
	v_add_f32_e32 v14, v14, v132
	v_add_f32_e32 v14, v14, v133
	v_add_f32_e32 v14, v14, v134
	v_add_f32_e32 v14, v14, v135
	v_cvt_pk_f16_f32 v66, v132, v133
	v_cvt_pk_f16_f32 v67, v134, v135
	ds_write_b64 v8, v[66:67] offset:288
	v_sub_f32_e32 v136, v136, v13
	v_sub_f32_e32 v137, v137, v13
	v_sub_f32_e32 v138, v138, v13
	v_sub_f32_e32 v139, v139, v13
	v_mul_f32_e32 v136, 0x3fb8aa3b, v136
	v_mul_f32_e32 v137, 0x3fb8aa3b, v137
	v_mul_f32_e32 v138, 0x3fb8aa3b, v138
	v_mul_f32_e32 v139, 0x3fb8aa3b, v139
	v_exp_f32_e32 v136, v136
	v_exp_f32_e32 v137, v137
	v_exp_f32_e32 v138, v138
	v_exp_f32_e32 v139, v139
	s_nop 0
	v_add_f32_e32 v14, v14, v136
	v_add_f32_e32 v14, v14, v137
	v_add_f32_e32 v14, v14, v138
	v_add_f32_e32 v14, v14, v139
	v_cvt_pk_f16_f32 v64, v136, v137
	v_cvt_pk_f16_f32 v65, v138, v139
	ds_write_b64 v8, v[64:65] offset:320
	v_sub_f32_e32 v140, v140, v13
	v_sub_f32_e32 v141, v141, v13
	v_sub_f32_e32 v142, v142, v13
	v_sub_f32_e32 v143, v143, v13
	v_mul_f32_e32 v140, 0x3fb8aa3b, v140
	v_mul_f32_e32 v141, 0x3fb8aa3b, v141
	v_mul_f32_e32 v142, 0x3fb8aa3b, v142
	v_mul_f32_e32 v143, 0x3fb8aa3b, v143
	v_exp_f32_e32 v140, v140
	v_exp_f32_e32 v141, v141
	v_exp_f32_e32 v142, v142
	v_exp_f32_e32 v143, v143
	s_nop 0
	v_add_f32_e32 v14, v14, v140
	v_add_f32_e32 v14, v14, v141
	v_add_f32_e32 v14, v14, v142
	v_add_f32_e32 v14, v14, v143
	v_cvt_pk_f16_f32 v66, v140, v141
	v_cvt_pk_f16_f32 v67, v142, v143
	ds_write_b64 v8, v[66:67] offset:352
	v_sub_f32_e32 v144, v144, v13
	v_sub_f32_e32 v145, v145, v13
	v_sub_f32_e32 v146, v146, v13
	v_sub_f32_e32 v147, v147, v13
	v_mul_f32_e32 v144, 0x3fb8aa3b, v144
	v_mul_f32_e32 v145, 0x3fb8aa3b, v145
	v_mul_f32_e32 v146, 0x3fb8aa3b, v146
	v_mul_f32_e32 v147, 0x3fb8aa3b, v147
	v_exp_f32_e32 v144, v144
	v_exp_f32_e32 v145, v145
	v_exp_f32_e32 v146, v146
	v_exp_f32_e32 v147, v147
	s_nop 0
	v_add_f32_e32 v14, v14, v144
	v_add_f32_e32 v14, v14, v145
	v_add_f32_e32 v14, v14, v146
	v_add_f32_e32 v14, v14, v147
	v_cvt_pk_f16_f32 v64, v144, v145
	v_cvt_pk_f16_f32 v65, v146, v147
	ds_write_b64 v8, v[64:65] offset:384
	v_sub_f32_e32 v148, v148, v13
	v_sub_f32_e32 v149, v149, v13
	v_sub_f32_e32 v150, v150, v13
	v_sub_f32_e32 v151, v151, v13
	v_mul_f32_e32 v148, 0x3fb8aa3b, v148
	v_mul_f32_e32 v149, 0x3fb8aa3b, v149
	v_mul_f32_e32 v150, 0x3fb8aa3b, v150
	v_mul_f32_e32 v151, 0x3fb8aa3b, v151
	v_exp_f32_e32 v148, v148
	v_exp_f32_e32 v149, v149
	v_exp_f32_e32 v150, v150
	v_exp_f32_e32 v151, v151
	s_nop 0
	v_add_f32_e32 v14, v14, v148
	v_add_f32_e32 v14, v14, v149
	v_add_f32_e32 v14, v14, v150
	v_add_f32_e32 v14, v14, v151
	v_cvt_pk_f16_f32 v66, v148, v149
	v_cvt_pk_f16_f32 v67, v150, v151
	ds_write_b64 v8, v[66:67] offset:416
	v_sub_f32_e32 v152, v152, v13
	v_sub_f32_e32 v153, v153, v13
	v_sub_f32_e32 v154, v154, v13
	v_sub_f32_e32 v155, v155, v13
	v_mul_f32_e32 v152, 0x3fb8aa3b, v152
	v_mul_f32_e32 v153, 0x3fb8aa3b, v153
	v_mul_f32_e32 v154, 0x3fb8aa3b, v154
	v_mul_f32_e32 v155, 0x3fb8aa3b, v155
	v_exp_f32_e32 v152, v152
	v_exp_f32_e32 v153, v153
	v_exp_f32_e32 v154, v154
	v_exp_f32_e32 v155, v155
	s_nop 0
	v_add_f32_e32 v14, v14, v152
	v_add_f32_e32 v14, v14, v153
	v_add_f32_e32 v14, v14, v154
	v_add_f32_e32 v14, v14, v155
	v_cvt_pk_f16_f32 v64, v152, v153
	v_cvt_pk_f16_f32 v65, v154, v155
	ds_write_b64 v8, v[64:65] offset:448
	v_sub_f32_e32 v156, v156, v13
	v_sub_f32_e32 v157, v157, v13
	v_sub_f32_e32 v158, v158, v13
	v_sub_f32_e32 v159, v159, v13
	v_mul_f32_e32 v156, 0x3fb8aa3b, v156
	v_mul_f32_e32 v157, 0x3fb8aa3b, v157
	v_mul_f32_e32 v158, 0x3fb8aa3b, v158
	v_mul_f32_e32 v159, 0x3fb8aa3b, v159
	v_exp_f32_e32 v156, v156
	v_exp_f32_e32 v157, v157
	v_exp_f32_e32 v158, v158
	v_exp_f32_e32 v159, v159
	s_nop 0
	v_add_f32_e32 v14, v14, v156
	v_add_f32_e32 v14, v14, v157
	v_add_f32_e32 v14, v14, v158
	v_add_f32_e32 v14, v14, v159
	v_cvt_pk_f16_f32 v66, v156, v157
	v_cvt_pk_f16_f32 v67, v158, v159
	ds_write_b64 v8, v[66:67] offset:480
	ds_bpermute_b32 v68, v11, v14
	s_waitcnt lgkmcnt(0)
	v_add_f32_e32 v14, v14, v68
	ds_bpermute_b32 v68, v12, v14
	s_waitcnt lgkmcnt(0)
	v_add_f32_e32 v14, v14, v68
	v_div_scale_f32 v64, s[34:35], v14, v14, 1.0
	v_div_scale_f32 v67, vcc, 1.0, v14, 1.0
	v_rcp_f32_e32 v65, v64
	s_nop 0
	v_fma_f32 v66, -v64, v65, 1.0
	v_fmac_f32_e32 v65, v66, v65
	v_mul_f32_e32 v68, v67, v65
	v_fma_f32 v69, -v64, v68, v67
	v_fmac_f32_e32 v68, v69, v65
	v_fma_f32 v64, -v64, v68, v67
	v_div_fmas_f32 v70, v64, v65, v68
	v_div_fixup_f32 v15, v70, v14, 1.0
	ds_read_b128 v[96:99], v9
	ds_read_b128 v[100:103], v9 offset:64
	ds_read_b128 v[104:107], v9 offset:128
	ds_read_b128 v[108:111], v9 offset:192
	ds_read_b128 v[112:115], v9 offset:256
	ds_read_b128 v[116:119], v9 offset:320
	ds_read_b128 v[120:123], v9 offset:384
	ds_read_b128 v[124:127], v9 offset:448
	s_barrier
; #define LAS __attribute__((address_space(3)))
; __device__ __forceinline__ void mem_attn_phase(int wv, const Args& A, LAS unsigned char* lds, int G) {
;     ...
;         for (int db = 0; db < 8; ++db) { f32x4 o = {0.f, 0.f, 0.f, 0.f};
; #pragma unroll
;             for (int ks = 0; ks < 8; ++ks) { const h16x8 vf = __builtin_bit_cast(h16x8, *(const u32x4*)(VTb + (size_t)(db * 16 + fr) * 256 + ks * 32 + fq * 8));
;                 const h16x8 pf = *(const LAS h16x8*)(Pw + fr * 264 + ks * 32 + fq * 8); o = __builtin_amdgcn_mfma_f32_16x16x32_f16(vf, pf, o, 0, 0, 0); }
;             h16x4 o4; o4[0] = (h16)(o[0] * inv); o4[1] = (h16)(o[1] * inv); o4[2] = (h16)(o[2] * inv); o4[3] = (h16)(o[3] * inv);
;             *(u32x2*)(MO + (row0 + fr) * 512 + h * 128 + db * 16 + fq * 4) = __builtin_bit_cast(u32x2, o4); }
	s_waitcnt vmcnt(0)
	ds_write_b128 v6, v[182:185]
	ds_write_b128 v6, v[186:189] offset:1024
	ds_write_b128 v6, v[190:193] offset:2048
	ds_write_b128 v6, v[194:197] offset:3072
	ds_write_b128 v6, v[198:201] offset:4096
	ds_write_b128 v6, v[202:205] offset:5120
	ds_write_b128 v6, v[206:209] offset:6144
	ds_write_b128 v6, v[210:213] offset:7168
	s_waitcnt lgkmcnt(0)
	s_barrier
	ds_read_b128 v[32:35], v7
	ds_read_b128 v[36:39], v7 offset:1024
	ds_read_b128 v[40:43], v7 offset:2048
	ds_read_b128 v[44:47], v7 offset:3072
	ds_read_b128 v[48:51], v7 offset:4096
	ds_read_b128 v[52:55], v7 offset:5120
	ds_read_b128 v[56:59], v7 offset:6144
	ds_read_b128 v[60:63], v7 offset:7168
	ds_read_b128 v[240:243], v7 offset:8192
	ds_read_b128 v[244:247], v7 offset:9216
	ds_read_b128 v[248:251], v7 offset:10240
	ds_read_b128 v[252:255], v7 offset:11264
	s_waitcnt lgkmcnt(11)
	v_mfma_f32_16x16x32_f16 v[128:131], v[32:35], v[96:99], 0
	ds_read_b128 v[32:35], v7 offset:12288
	s_waitcnt lgkmcnt(11)
	v_mfma_f32_16x16x32_f16 v[128:131], v[36:39], v[100:103], v[128:131]
	ds_read_b128 v[36:39], v7 offset:13312
	s_waitcnt lgkmcnt(11)
	v_mfma_f32_16x16x32_f16 v[128:131], v[40:43], v[104:107], v[128:131]
	ds_read_b128 v[40:43], v7 offset:14336
	s_waitcnt lgkmcnt(11)
	v_mfma_f32_16x16x32_f16 v[128:131], v[44:47], v[108:111], v[128:131]
	ds_read_b128 v[44:47], v7 offset:15360
	s_waitcnt lgkmcnt(11)
	v_mfma_f32_16x16x32_f16 v[128:131], v[48:51], v[112:115], v[128:131]
	ds_read_b128 v[48:51], v7 offset:16384
	s_waitcnt lgkmcnt(11)
	v_mfma_f32_16x16x32_f16 v[128:131], v[52:55], v[116:119], v[128:131]
	ds_read_b128 v[52:55], v7 offset:17408
	s_waitcnt lgkmcnt(11)
	v_mfma_f32_16x16x32_f16 v[128:131], v[56:59], v[120:123], v[128:131]
	ds_read_b128 v[56:59], v7 offset:18432
	s_waitcnt lgkmcnt(11)
	v_mfma_f32_16x16x32_f16 v[128:131], v[60:63], v[124:127], v[128:131]
	ds_read_b128 v[60:63], v7 offset:19456
	s_waitcnt lgkmcnt(11)
	v_mfma_f32_16x16x32_f16 v[132:135], v[240:243], v[96:99], 0
	ds_read_b128 v[240:243], v7 offset:20480
	s_waitcnt lgkmcnt(11)
	v_mfma_f32_16x16x32_f16 v[132:135], v[244:247], v[100:103], v[132:135]
	ds_read_b128 v[244:247], v7 offset:21504
	s_waitcnt lgkmcnt(11)
	v_mfma_f32_16x16x32_f16 v[132:135], v[248:251], v[104:107], v[132:135]
	ds_read_b128 v[248:251], v7 offset:22528
	s_waitcnt lgkmcnt(11)
	v_mfma_f32_16x16x32_f16 v[132:135], v[252:255], v[108:111], v[132:135]
	ds_read_b128 v[252:255], v7 offset:23552
	s_waitcnt lgkmcnt(11)
	v_mul_f32_e32 v128, v128, v15
	v_mul_f32_e32 v129, v129, v15
	v_mul_f32_e32 v130, v130, v15
	v_mul_f32_e32 v131, v131, v15
	v_cvt_pk_f16_f32 v136, v128, v129
	v_cvt_pk_f16_f32 v137, v130, v131
	global_store_dwordx2 v10, v[136:137], s[94:95]
	v_mfma_f32_16x16x32_f16 v[132:135], v[32:35], v[112:115], v[132:135]
	ds_read_b128 v[32:35], v7 offset:24576
	s_waitcnt lgkmcnt(11)
	v_mfma_f32_16x16x32_f16 v[132:135], v[36:39], v[116:119], v[132:135]
	ds_read_b128 v[36:39], v7 offset:25600
	s_waitcnt lgkmcnt(11)
	v_mfma_f32_16x16x32_f16 v[132:135], v[40:43], v[120:123], v[132:135]
	ds_read_b128 v[40:43], v7 offset:26624
	s_waitcnt lgkmcnt(11)
	v_mfma_f32_16x16x32_f16 v[132:135], v[44:47], v[124:127], v[132:135]
	ds_read_b128 v[44:47], v7 offset:27648
	s_waitcnt lgkmcnt(11)
	v_mfma_f32_16x16x32_f16 v[128:131], v[48:51], v[96:99], 0
	ds_read_b128 v[48:51], v7 offset:28672
	s_waitcnt lgkmcnt(11)
	v_mfma_f32_16x16x32_f16 v[128:131], v[52:55], v[100:103], v[128:131]
	ds_read_b128 v[52:55], v7 offset:29696
	s_waitcnt lgkmcnt(11)
	v_mfma_f32_16x16x32_f16 v[128:131], v[56:59], v[104:107], v[128:131]
	ds_read_b128 v[56:59], v7 offset:30720
	s_waitcnt lgkmcnt(11)
	v_mfma_f32_16x16x32_f16 v[128:131], v[60:63], v[108:111], v[128:131]
	ds_read_b128 v[60:63], v7 offset:31744
	s_waitcnt lgkmcnt(11)
	v_mul_f32_e32 v132, v132, v15
	v_mul_f32_e32 v133, v133, v15
	v_mul_f32_e32 v134, v134, v15
	v_mul_f32_e32 v135, v135, v15
	v_cvt_pk_f16_f32 v138, v132, v133
	v_cvt_pk_f16_f32 v139, v134, v135
	global_store_dwordx2 v10, v[138:139], s[94:95] offset:32
	v_mfma_f32_16x16x32_f16 v[128:131], v[240:243], v[112:115], v[128:131]
	ds_read_b128 v[240:243], v7 offset:32768
	s_waitcnt lgkmcnt(11)
	v_mfma_f32_16x16x32_f16 v[128:131], v[244:247], v[116:119], v[128:131]
	ds_read_b128 v[244:247], v7 offset:33792
	s_waitcnt lgkmcnt(11)
	v_mfma_f32_16x16x32_f16 v[128:131], v[248:251], v[120:123], v[128:131]
	ds_read_b128 v[248:251], v7 offset:34816
	s_waitcnt lgkmcnt(11)
	v_mfma_f32_16x16x32_f16 v[128:131], v[252:255], v[124:127], v[128:131]
	ds_read_b128 v[252:255], v7 offset:35840
	s_waitcnt lgkmcnt(11)
	v_mfma_f32_16x16x32_f16 v[132:135], v[32:35], v[96:99], 0
	ds_read_b128 v[32:35], v7 offset:36864
	s_waitcnt lgkmcnt(11)
	v_mfma_f32_16x16x32_f16 v[132:135], v[36:39], v[100:103], v[132:135]
	ds_read_b128 v[36:39], v7 offset:37888
	s_waitcnt lgkmcnt(11)
	v_mfma_f32_16x16x32_f16 v[132:135], v[40:43], v[104:107], v[132:135]
	ds_read_b128 v[40:43], v7 offset:38912
	s_waitcnt lgkmcnt(11)
	v_mfma_f32_16x16x32_f16 v[132:135], v[44:47], v[108:111], v[132:135]
	ds_read_b128 v[44:47], v7 offset:39936
	s_waitcnt lgkmcnt(11)
	v_mul_f32_e32 v128, v128, v15
	v_mul_f32_e32 v129, v129, v15
	v_mul_f32_e32 v130, v130, v15
	v_mul_f32_e32 v131, v131, v15
	v_cvt_pk_f16_f32 v136, v128, v129
	v_cvt_pk_f16_f32 v137, v130, v131
	global_store_dwordx2 v10, v[136:137], s[94:95] offset:64
	v_mfma_f32_16x16x32_f16 v[132:135], v[48:51], v[112:115], v[132:135]
	ds_read_b128 v[48:51], v7 offset:40960
	s_waitcnt lgkmcnt(11)
	v_mfma_f32_16x16x32_f16 v[132:135], v[52:55], v[116:119], v[132:135]
	ds_read_b128 v[52:55], v7 offset:41984
	s_waitcnt lgkmcnt(11)
; #define LAS __attribute__((address_space(3)))
; __device__ __forceinline__ void mem_attn_phase(int wv, const Args& A, LAS unsigned char* lds, int G) {
;     ...
;     for (int wu = blockIdx.x * 8 + w; wu < (MT / 16) * 4; wu += G * 8) {
;     ...
;         for (int db = 0; db < 8; ++db) { f32x4 o = {0.f, 0.f, 0.f, 0.f};
; #pragma unroll
;             for (int ks = 0; ks < 8; ++ks) { const h16x8 vf = __builtin_bit_cast(h16x8, *(const u32x4*)(VTb + (size_t)(db * 16 + fr) * 256 + ks * 32 + fq * 8));
;                 const h16x8 pf = *(const LAS h16x8*)(Pw + fr * 264 + ks * 32 + fq * 8); o = __builtin_amdgcn_mfma_f32_16x16x32_f16(vf, pf, o, 0, 0, 0); }
;             h16x4 o4; o4[0] = (h16)(o[0] * inv); o4[1] = (h16)(o[1] * inv); o4[2] = (h16)(o[2] * inv); o4[3] = (h16)(o[3] * inv);
;             *(u32x2*)(MO + (row0 + fr) * 512 + h * 128 + db * 16 + fq * 4) = __builtin_bit_cast(u32x2, o4); }
	v_mfma_f32_16x16x32_f16 v[132:135], v[56:59], v[120:123], v[132:135]
	ds_read_b128 v[56:59], v7 offset:43008
	s_waitcnt lgkmcnt(11)
	v_mfma_f32_16x16x32_f16 v[132:135], v[60:63], v[124:127], v[132:135]
	ds_read_b128 v[60:63], v7 offset:44032
	s_waitcnt lgkmcnt(11)
	v_mfma_f32_16x16x32_f16 v[128:131], v[240:243], v[96:99], 0
	ds_read_b128 v[240:243], v7 offset:45056
	s_waitcnt lgkmcnt(11)
	v_mfma_f32_16x16x32_f16 v[128:131], v[244:247], v[100:103], v[128:131]
	ds_read_b128 v[244:247], v7 offset:46080
	s_waitcnt lgkmcnt(11)
	v_mfma_f32_16x16x32_f16 v[128:131], v[248:251], v[104:107], v[128:131]
	ds_read_b128 v[248:251], v7 offset:47104
	s_waitcnt lgkmcnt(11)
	v_mfma_f32_16x16x32_f16 v[128:131], v[252:255], v[108:111], v[128:131]
	ds_read_b128 v[252:255], v7 offset:48128
	s_waitcnt lgkmcnt(11)
	v_mul_f32_e32 v132, v132, v15
	v_mul_f32_e32 v133, v133, v15
	v_mul_f32_e32 v134, v134, v15
	v_mul_f32_e32 v135, v135, v15
	v_cvt_pk_f16_f32 v138, v132, v133
	v_cvt_pk_f16_f32 v139, v134, v135
	global_store_dwordx2 v10, v[138:139], s[94:95] offset:96
	v_mfma_f32_16x16x32_f16 v[128:131], v[32:35], v[112:115], v[128:131]
	ds_read_b128 v[32:35], v7 offset:49152
	s_waitcnt lgkmcnt(11)
	v_mfma_f32_16x16x32_f16 v[128:131], v[36:39], v[116:119], v[128:131]
	ds_read_b128 v[36:39], v7 offset:50176
	s_waitcnt lgkmcnt(11)
	v_mfma_f32_16x16x32_f16 v[128:131], v[40:43], v[120:123], v[128:131]
	ds_read_b128 v[40:43], v7 offset:51200
	s_waitcnt lgkmcnt(11)
	v_mfma_f32_16x16x32_f16 v[128:131], v[44:47], v[124:127], v[128:131]
	ds_read_b128 v[44:47], v7 offset:52224
	s_waitcnt lgkmcnt(11)
	v_mfma_f32_16x16x32_f16 v[132:135], v[48:51], v[96:99], 0
	ds_read_b128 v[48:51], v7 offset:53248
	s_waitcnt lgkmcnt(11)
	v_mfma_f32_16x16x32_f16 v[132:135], v[52:55], v[100:103], v[132:135]
	ds_read_b128 v[52:55], v7 offset:54272
	s_waitcnt lgkmcnt(11)
	v_mfma_f32_16x16x32_f16 v[132:135], v[56:59], v[104:107], v[132:135]
	ds_read_b128 v[56:59], v7 offset:55296
	s_waitcnt lgkmcnt(11)
	v_mfma_f32_16x16x32_f16 v[132:135], v[60:63], v[108:111], v[132:135]
	ds_read_b128 v[60:63], v7 offset:56320
	s_waitcnt lgkmcnt(11)
	v_mul_f32_e32 v128, v128, v15
	v_mul_f32_e32 v129, v129, v15
	v_mul_f32_e32 v130, v130, v15
	v_mul_f32_e32 v131, v131, v15
	v_cvt_pk_f16_f32 v136, v128, v129
	v_cvt_pk_f16_f32 v137, v130, v131
	global_store_dwordx2 v10, v[136:137], s[94:95] offset:128
	v_mfma_f32_16x16x32_f16 v[132:135], v[240:243], v[112:115], v[132:135]
	ds_read_b128 v[240:243], v7 offset:57344
	s_waitcnt lgkmcnt(11)
	v_mfma_f32_16x16x32_f16 v[132:135], v[244:247], v[116:119], v[132:135]
	ds_read_b128 v[244:247], v7 offset:58368
	s_waitcnt lgkmcnt(11)
	v_mfma_f32_16x16x32_f16 v[132:135], v[248:251], v[120:123], v[132:135]
	ds_read_b128 v[248:251], v7 offset:59392
	s_waitcnt lgkmcnt(11)
	v_mfma_f32_16x16x32_f16 v[132:135], v[252:255], v[124:127], v[132:135]
	ds_read_b128 v[252:255], v7 offset:60416
	s_waitcnt lgkmcnt(11)
	v_mfma_f32_16x16x32_f16 v[128:131], v[32:35], v[96:99], 0
	ds_read_b128 v[32:35], v7 offset:61440
	s_waitcnt lgkmcnt(11)
	v_mfma_f32_16x16x32_f16 v[128:131], v[36:39], v[100:103], v[128:131]
	ds_read_b128 v[36:39], v7 offset:62464
	s_waitcnt lgkmcnt(11)
	v_mfma_f32_16x16x32_f16 v[128:131], v[40:43], v[104:107], v[128:131]
	ds_read_b128 v[40:43], v7 offset:63488
	s_waitcnt lgkmcnt(11)
	v_mfma_f32_16x16x32_f16 v[128:131], v[44:47], v[108:111], v[128:131]
	ds_read_b128 v[44:47], v7 offset:64512
	s_waitcnt lgkmcnt(11)
	v_mul_f32_e32 v132, v132, v15
	v_mul_f32_e32 v133, v133, v15
	v_mul_f32_e32 v134, v134, v15
	v_mul_f32_e32 v135, v135, v15
	v_cvt_pk_f16_f32 v138, v132, v133
	v_cvt_pk_f16_f32 v139, v134, v135
	global_store_dwordx2 v10, v[138:139], s[94:95] offset:160
	v_mfma_f32_16x16x32_f16 v[128:131], v[48:51], v[112:115], v[128:131]
	s_waitcnt lgkmcnt(10)
	v_mfma_f32_16x16x32_f16 v[128:131], v[52:55], v[116:119], v[128:131]
	s_waitcnt lgkmcnt(9)
	v_mfma_f32_16x16x32_f16 v[128:131], v[56:59], v[120:123], v[128:131]
	s_waitcnt lgkmcnt(8)
	v_mfma_f32_16x16x32_f16 v[128:131], v[60:63], v[124:127], v[128:131]
	s_waitcnt lgkmcnt(7)
	v_mfma_f32_16x16x32_f16 v[132:135], v[240:243], v[96:99], 0
	s_waitcnt lgkmcnt(6)
	v_mfma_f32_16x16x32_f16 v[132:135], v[244:247], v[100:103], v[132:135]
	s_waitcnt lgkmcnt(5)
	v_mfma_f32_16x16x32_f16 v[132:135], v[248:251], v[104:107], v[132:135]
	s_waitcnt lgkmcnt(4)
	v_mfma_f32_16x16x32_f16 v[132:135], v[252:255], v[108:111], v[132:135]
	s_waitcnt lgkmcnt(3)
	v_mul_f32_e32 v128, v128, v15
	v_mul_f32_e32 v129, v129, v15
	v_mul_f32_e32 v130, v130, v15
	v_mul_f32_e32 v131, v131, v15
	v_cvt_pk_f16_f32 v136, v128, v129
	v_cvt_pk_f16_f32 v137, v130, v131
	global_store_dwordx2 v10, v[136:137], s[94:95] offset:192
	v_mfma_f32_16x16x32_f16 v[132:135], v[32:35], v[112:115], v[132:135]
	s_waitcnt lgkmcnt(2)
	v_mfma_f32_16x16x32_f16 v[132:135], v[36:39], v[116:119], v[132:135]
	s_waitcnt lgkmcnt(1)
	v_mfma_f32_16x16x32_f16 v[132:135], v[40:43], v[120:123], v[132:135]
	s_waitcnt lgkmcnt(0)
	v_mfma_f32_16x16x32_f16 v[132:135], v[44:47], v[124:127], v[132:135]
	s_nop 7
	s_nop 1
	v_mul_f32_e32 v132, v132, v15
	v_mul_f32_e32 v133, v133, v15
	v_mul_f32_e32 v134, v134, v15
	v_mul_f32_e32 v135, v135, v15
	v_cvt_pk_f16_f32 v138, v132, v133
	v_cvt_pk_f16_f32 v139, v134, v135
	global_store_dwordx2 v10, v[138:139], s[94:95] offset:224
	s_add_i32 s71, s71, 1
	s_cmp_lt_u32 s71, 4
	s_cbranch_scc1 .Lma_round
; #define LAS __attribute__((address_space(3)))
; __device__ __forceinline__ int opaque_tid(int wv) { int t = wv * 64 + (int)__builtin_amdgcn_mbcnt_hi(~0u, __builtin_amdgcn_mbcnt_lo(~0u, 0u)); asm volatile("" : "+v"(t)); return t; }
; __device__ __forceinline__ void mem_attn_phase(int wv, const Args& A, LAS unsigned char* lds, int G) {
;     const int tid = opaque_tid(wv), lane = tid & 63, w = tid >> 6, fr = lane & 15, fq = lane >> 4;
;     unsigned char* ws = A.ws;
;     const h16* MQ = (const h16*)(ws + WS_MQ); h16* MO = (h16*)(ws + WS_MO);
;     LAS h16* Pw = (LAS h16*)(lds + w * 8448);
;     for (int wu = blockIdx.x * 8 + w; wu < (MT / 16) * 4; wu += G * 8) {
;         const int blk = wu >> 3; const int h = blk & 3, tile = (blk >> 2) * 8 + (wu & 7); const size_t row0 = (size_t)tile * 16;
;         const h16* Kb; const h16* VTb;
;         if (row0 < NP) { const int b = (int)(row0 >> 14); Kb = (const h16*)(ws + WS_MK16) + (size_t)b * 256 * 512; VTb = (const h16*)(ws + WS_MVT) + (size_t)(b * 4 + h) * 32768; }
;         else { const int bs = (int)((row0 - NP) >> 6); Kb = (const h16*)(ws + WS_CMK) + (size_t)bs * 256 * 512; VTb = (const h16*)(ws + WS_CMVT) + (size_t)(bs * 4 + h) * 32768; }
	s_waitcnt vmcnt(0)
	v_mov_b32_e32 v0, v170
	s_movk_i32 s0, 0x2080
	v_ashrrev_i32_e32 v1, 6, v0
	v_add_u32_e32 v77, s81, v1
	v_add_u32_e32 v77, 0x2000, v77
	v_cmp_gt_i32_e32 vcc, s0, v77
	s_and_saveexec_b64 s[6:7], vcc
	s_cbranch_execz .LBB0_2406
	s_add_u32 s8, s44, 0x324c1000
	s_addc_u32 s9, s45, 0
	s_add_u32 s10, s44, 0x34541000
	s_addc_u32 s11, s45, 0
	s_add_u32 s12, s44, 0x3d64d000
	s_addc_u32 s13, s45, 0
	s_add_u32 s14, s44, 0x3d84d000
	s_movk_i32 s0, 0x2100
	s_addc_u32 s15, s45, 0
	v_mul_lo_u32 v1, v1, s0
	v_bfe_u32 v3, v0, 4, 2
	v_and_b32_e32 v76, 15, v0
	s_add_u32 s16, s44, 0x3cc4d000
	v_add_u32_e32 v1, 0, v1
	s_addc_u32 s17, s45, 0
	v_lshlrev_b32_e32 v2, 3, v3
	v_mul_u32_u24_e32 v5, 0x210, v76
	s_add_u32 s18, s44, 0x3cccd000
	v_mov_b32_e32 v79, 0
	v_lshlrev_b32_e32 v4, 9, v76
	v_add3_u32 v92, v1, v5, v2
	v_lshlrev_b32_e32 v6, 8, v76
	v_lshlrev_b32_e32 v8, 2, v3
	s_movk_i32 s24, 0x8000
	s_addc_u32 s19, s45, 0
	v_bfe_u32 v93, v0, 6, 3
	s_mov_b64 s[20:21], 0
	s_mov_b64 s[22:23], 0x7fff
	s_mov_b32 s25, 63
	v_lshlrev_b32_e32 v80, 1, v2
	v_mov_b32_e32 v81, v79
	v_lshlrev_b32_e32 v82, 1, v4
	v_mov_b32_e32 v83, v79
	s_movk_i32 s0, 0x4000
	s_mov_b32 s1, 0xff800000
	s_mov_b32 s3, 0x8000
	s_mov_b32 s4, 0xc000
	s_mov_b32 s5, 0x10000
	s_mov_b32 s28, 0x14000
	s_mov_b32 s29, 0x18000
	s_mov_b32 s30, 0x1c000
	s_mov_b32 s31, 0x20000
	s_mov_b32 s33, 0x24000
	s_mov_b32 s34, 0x28000
	s_mov_b32 s35, 0x2c000
	s_mov_b32 s36, 0x30000
	s_mov_b32 s37, 0x34000
	s_mov_b32 s38, 0x38000
	s_mov_b32 s39, 0x3c000
	v_lshlrev_b32_e32 v84, 1, v8
	v_mov_b32_e32 v85, v79
	v_lshlrev_b32_e32 v86, 1, v6
	v_mov_b32_e32 v87, v79
	v_add_u32_e32 v94, v92, v2
	s_movk_i32 s40, 0x2000
	s_movk_i32 s41, 0x6000
	s_mov_b32 s42, 0xa000
	s_mov_b32 s43, 0xe000
	s_movk_i32 s48, 0x207f
	s_branch .LBB0_2402
